# write-through (sc1) on the widened 16-byte attention output stores
# baseline (speedup 1.0000x reference)
; __device__ __forceinline__ unsigned pk_bf16(float lo, float hi) { return pg8::cvt_pk_bf16(lo, hi); }
; template <int DV, int NMAP>
; __device__ __forceinline__ void attn_unit(LAS unsigned char* lds, const bf16_t* U, bf16_t* MIX, const float* logf, int b, int h, int qb, float lam, float slope2, const float* gn, float outscale, const int tid) {
;     ...
;     __syncthreads();
;     const float inv = 1.0f / (l_run + __shfl_xor(l_run, 32));
;     const size_t orow = (rowbase + qrow0 + r32) * DM;
;     if (NMAP == 1) {
; #pragma unroll
;         for (int d = 0; d < NDB; ++d)
; #pragma unroll
;             for (int g = 0; g < 4; ++g) { u32x2 w; w.x = pk_bf16(o[d][4 * g] * inv, o[d][4 * g + 1] * inv); w.y = pk_bf16(o[d][4 * g + 2] * inv, o[d][4 * g + 3] * inv);
;                 *(u32x2*)(MIX + orow + 64 * h + 32 * d + 8 * g + 4 * hi) = w; }
;         __syncthreads();
.LBB0_205:
	ds_bpermute_b32 v0, v224, v105
	s_lshl_b32 s20, s33, 1
	s_waitcnt lgkmcnt(0)
	s_barrier
	v_add_f32_e32 v0, v105, v0
	v_div_scale_f32 v34, s[30:31], v0, v0, 1.0
	v_rcp_f32_e32 v35, v34
	v_div_scale_f32 v36, vcc, 1.0, v0, 1.0
	v_readlane_b32 s30, v250, 34
	v_fma_f32 v37, -v34, v35, 1.0
	v_fmac_f32_e32 v35, v37, v35
	v_mul_f32_e32 v37, v36, v35
	v_fma_f32 v38, -v34, v37, v36
	v_fmac_f32_e32 v37, v38, v35
	v_fma_f32 v34, -v34, v37, v36
	v_div_fmas_f32 v34, v34, v35, v37
	v_readlane_b32 s31, v250, 35
	s_add_u32 s30, s30, s20
	v_div_fixup_f32 v36, v34, v0, 1.0
	s_addc_u32 s31, s31, 0
	v_lshlrev_b64 v[34:35], 11, v[98:99]
	v_lshl_add_u64 v[34:35], s[30:31], 0, v[34:35]
	v_lshlrev_b32_e32 v0, 1, v130
	v_lshl_add_u64 v[34:35], v[34:35], 0, v[0:1]
	v_lshl_add_u64 v[34:35], v[34:35], 0, v[0:1]
	v_mul_f32_e32 v56, v2, v36
	v_mul_f32_e32 v57, v3, v36
	v_cvt_pk_bf16_f32 v40, v56, v57
	v_mul_f32_e32 v56, v4, v36
	v_mul_f32_e32 v57, v5, v36
	v_cvt_pk_bf16_f32 v41, v56, v57
	v_mul_f32_e32 v56, v6, v36
	v_mul_f32_e32 v57, v7, v36
	v_cvt_pk_bf16_f32 v42, v56, v57
	v_mul_f32_e32 v56, v8, v36
	v_mul_f32_e32 v57, v9, v36
	v_cvt_pk_bf16_f32 v43, v56, v57
	s_nop 1
	v_permlane32_swap_b32_e32 v40, v42
	v_permlane32_swap_b32_e32 v41, v43
	global_store_dwordx4 v[34:35], v[40:43], off sc1
	v_mul_f32_e32 v56, v10, v36
	v_mul_f32_e32 v57, v11, v36
	v_cvt_pk_bf16_f32 v44, v56, v57
	v_mul_f32_e32 v56, v12, v36
	v_mul_f32_e32 v57, v13, v36
	v_cvt_pk_bf16_f32 v45, v56, v57
	v_mul_f32_e32 v56, v14, v36
	v_mul_f32_e32 v57, v15, v36
	v_cvt_pk_bf16_f32 v46, v56, v57
	v_mul_f32_e32 v56, v16, v36
	v_mul_f32_e32 v57, v17, v36
	v_cvt_pk_bf16_f32 v47, v56, v57
	s_nop 1
	v_permlane32_swap_b32_e32 v44, v46
	v_permlane32_swap_b32_e32 v45, v47
	global_store_dwordx4 v[34:35], v[44:47], off offset:32 sc1
	v_mul_f32_e32 v56, v18, v36
	v_mul_f32_e32 v57, v19, v36
	v_cvt_pk_bf16_f32 v48, v56, v57
	v_mul_f32_e32 v56, v20, v36
	v_mul_f32_e32 v57, v21, v36
	v_cvt_pk_bf16_f32 v49, v56, v57
	v_mul_f32_e32 v56, v22, v36
	v_mul_f32_e32 v57, v23, v36
	v_cvt_pk_bf16_f32 v50, v56, v57
	v_mul_f32_e32 v56, v24, v36
	v_mul_f32_e32 v57, v25, v36
	v_cvt_pk_bf16_f32 v51, v56, v57
	s_nop 1
	v_permlane32_swap_b32_e32 v48, v50
	v_permlane32_swap_b32_e32 v49, v51
	global_store_dwordx4 v[34:35], v[48:51], off offset:64 sc1
	v_mul_f32_e32 v56, v26, v36
	v_mul_f32_e32 v57, v27, v36
	v_cvt_pk_bf16_f32 v52, v56, v57
	v_mul_f32_e32 v56, v28, v36
	v_mul_f32_e32 v57, v29, v36
	v_cvt_pk_bf16_f32 v53, v56, v57
	v_mul_f32_e32 v56, v30, v36
	v_mul_f32_e32 v57, v31, v36
	v_cvt_pk_bf16_f32 v54, v56, v57
	v_mul_f32_e32 v56, v32, v36
	v_mul_f32_e32 v57, v33, v36
	v_cvt_pk_bf16_f32 v55, v56, v57
	s_nop 1
	v_permlane32_swap_b32_e32 v52, v54
	v_permlane32_swap_b32_e32 v53, v55
	global_store_dwordx4 v[34:35], v[52:55], off offset:96 sc1
	s_mov_b64 s[30:31], 0
	s_barrier

; template <int DV, int NMAP>
; __device__ __forceinline__ void attn_unit(LAS unsigned char* lds, const bf16_t* U, bf16_t* MIX, const float* logf, int b, int h, int qb, float lam, float slope2, const float* gn, float outscale, const int tid) {
;     ...
;         __syncthreads();
;         if (map == 0) {
;             float ss = 0.f;
; #pragma unroll
;             for (int d = 0; d < NDB; ++d)
; #pragma unroll
;                 for (int r = 0; r < 16; ++r) { const float v = o[d][r] * inv - ex[(d * 16 + r) * 64]; o[d][r] = v; ss += v * v; }
;             ss += __shfl_xor(ss, 32);
.LBB0_231:
	s_cmpk_gt_u32 s33, 0xff
	s_waitcnt lgkmcnt(0)
	s_barrier
	s_cbranch_scc1 .LBB0_175
	global_load_dwordx4 v[80:83], v[132:133], off
	global_load_dwordx4 v[84:87], v[132:133], off offset:32
	global_load_dwordx4 v[88:91], v[132:133], off offset:64
	global_load_dwordx4 v[92:95], v[132:133], off offset:96
	global_load_dwordx4 v[96:99], v[132:133], off offset:128
	global_load_dwordx4 v[100:103], v[132:133], off offset:160
	global_load_dwordx4 v[104:107], v[132:133], off offset:192
	global_load_dwordx4 v[108:111], v[132:133], off offset:224
	global_load_dwordx4 v[112:115], v[132:133], off offset:256
	global_load_dwordx4 v[116:119], v[132:133], off offset:288
	global_load_dwordx4 v[152:155], v[132:133], off offset:320
	global_load_dwordx4 v[156:159], v[132:133], off offset:352
	global_load_dwordx4 v[160:163], v[132:133], off offset:384
	global_load_dwordx4 v[164:167], v[132:133], off offset:416
	global_load_dwordx4 v[168:171], v[132:133], off offset:448
	global_load_dwordx4 v[172:175], v[132:133], off offset:480
	ds_read2st64_b32 v[66:67], v77 offset0:33 offset1:34
	ds_read2st64_b32 v[68:69], v77 offset0:35 offset1:36
	ds_read2st64_b32 v[70:71], v77 offset0:53 offset1:54
	s_lshl_b32 s20, s27, 1
	s_waitcnt lgkmcnt(2)
	v_fma_f32 v66, v50, v0, -v66
	v_fma_f32 v50, v51, v0, -v67
	s_waitcnt lgkmcnt(1)
	v_fma_f32 v51, v52, v0, -v68
	v_fma_f32 v52, v53, v0, -v69
	ds_read2st64_b32 v[68:69], v77 offset0:37 offset1:38
	v_mul_f32_e32 v78, v50, v50
	v_fmac_f32_e32 v78, v66, v66
	v_fmac_f32_e32 v78, v51, v51
	v_fmac_f32_e32 v78, v52, v52
	s_waitcnt lgkmcnt(0)
	v_fma_f32 v53, v54, v0, -v68
	v_fma_f32 v54, v55, v0, -v69
	ds_read2st64_b32 v[68:69], v77 offset0:39 offset1:40
	v_fmac_f32_e32 v78, v53, v53
	v_fmac_f32_e32 v78, v54, v54
	s_waitcnt lgkmcnt(0)
	v_fma_f32 v55, v56, v0, -v68
	v_fma_f32 v56, v57, v0, -v69
	ds_read2st64_b32 v[68:69], v77 offset0:41 offset1:42
	v_fmac_f32_e32 v78, v55, v55
	v_fmac_f32_e32 v78, v56, v56
	s_waitcnt lgkmcnt(0)
	v_fma_f32 v58, v58, v0, -v68
	v_fma_f32 v57, v59, v0, -v69
	ds_read2st64_b32 v[68:69], v77 offset0:43 offset1:44
	v_fmac_f32_e32 v78, v58, v58
	v_fmac_f32_e32 v78, v57, v57
	s_waitcnt lgkmcnt(0)
	v_fma_f32 v67, v60, v0, -v68
	v_fma_f32 v60, v61, v0, -v69
	ds_read2st64_b32 v[68:69], v77 offset0:45 offset1:46
	v_fmac_f32_e32 v78, v67, v67
	v_fmac_f32_e32 v78, v60, v60
	s_waitcnt lgkmcnt(0)
	v_fma_f32 v61, v62, v0, -v68
	v_fma_f32 v59, v63, v0, -v69
	ds_read2st64_b32 v[62:63], v77 offset0:47 offset1:48
	v_fmac_f32_e32 v78, v61, v61
	v_fmac_f32_e32 v78, v59, v59
	s_waitcnt lgkmcnt(0)
	v_fma_f32 v68, v64, v0, -v62
	v_fma_f32 v63, v65, v0, -v63
	ds_read2st64_b32 v[64:65], v77 offset0:49 offset1:50
	v_fmac_f32_e32 v78, v68, v68
	v_fmac_f32_e32 v78, v63, v63
	s_waitcnt lgkmcnt(0)
	v_fma_f32 v62, v34, v0, -v64
	v_fma_f32 v34, v35, v0, -v65
	ds_read2st64_b32 v[64:65], v77 offset0:51 offset1:52
	v_fma_f32 v35, v39, v0, -v71
	v_fmac_f32_e32 v78, v62, v62
	v_fmac_f32_e32 v78, v34, v34
	s_waitcnt lgkmcnt(0)
	v_fma_f32 v64, v36, v0, -v64
	v_fma_f32 v36, v37, v0, -v65
	v_fma_f32 v37, v38, v0, -v70
	ds_read2st64_b32 v[38:39], v77 offset0:55 offset1:56
	v_fmac_f32_e32 v78, v64, v64
	v_fmac_f32_e32 v78, v36, v36
	v_fmac_f32_e32 v78, v37, v37
	v_fmac_f32_e32 v78, v35, v35
	s_waitcnt lgkmcnt(0)
	v_fma_f32 v69, v40, v0, -v38
	v_fma_f32 v65, v41, v0, -v39
	ds_read2st64_b32 v[40:41], v77 offset0:57 offset1:58
	v_fmac_f32_e32 v78, v69, v69
	v_fmac_f32_e32 v78, v65, v65
	s_waitcnt lgkmcnt(0)
	v_fma_f32 v39, v42, v0, -v40
	v_fma_f32 v38, v43, v0, -v41
	ds_read2st64_b32 v[40:41], v77 offset0:59 offset1:60
	v_fmac_f32_e32 v78, v39, v39
	v_fmac_f32_e32 v78, v38, v38
	s_waitcnt lgkmcnt(0)
	v_fma_f32 v43, v44, v0, -v40
	v_fma_f32 v41, v45, v0, -v41
	ds_read2st64_b32 v[44:45], v77 offset0:61 offset1:62
	v_fmac_f32_e32 v78, v43, v43
	v_fmac_f32_e32 v78, v41, v41
	s_waitcnt lgkmcnt(0)
	v_fma_f32 v42, v46, v0, -v44
	v_fma_f32 v40, v47, v0, -v45
	ds_read2st64_b32 v[44:45], v77 offset0:63 offset1:64
	v_fmac_f32_e32 v78, v42, v42
	v_fmac_f32_e32 v78, v40, v40
	s_waitcnt lgkmcnt(0)
	v_fma_f32 v47, v48, v0, -v44
	v_fma_f32 v45, v49, v0, -v45
	ds_read2st64_b32 v[48:49], v77 offset0:65 offset1:66
	v_fmac_f32_e32 v78, v47, v47
	v_fmac_f32_e32 v78, v45, v45
	s_waitcnt lgkmcnt(0)
	v_fma_f32 v44, v18, v0, -v48
	v_fma_f32 v18, v19, v0, -v49
	ds_read2st64_b32 v[48:49], v77 offset0:67 offset1:68
	v_fmac_f32_e32 v78, v44, v44
	v_fmac_f32_e32 v78, v18, v18
	s_waitcnt lgkmcnt(0)
	v_fma_f32 v46, v20, v0, -v48
	v_fma_f32 v20, v21, v0, -v49
	ds_read2st64_b32 v[48:49], v77 offset0:69 offset1:70
	v_fmac_f32_e32 v78, v46, v46
	v_fmac_f32_e32 v78, v20, v20
	s_waitcnt lgkmcnt(0)
	v_fma_f32 v21, v22, v0, -v48
	v_fma_f32 v19, v23, v0, -v49
	ds_read2st64_b32 v[22:23], v77 offset0:71 offset1:72
	v_fmac_f32_e32 v78, v21, v21
	v_fmac_f32_e32 v78, v19, v19
	s_waitcnt lgkmcnt(0)
	v_fma_f32 v49, v24, v0, -v22
	v_fma_f32 v48, v25, v0, -v23
	ds_read2st64_b32 v[24:25], v77 offset0:73 offset1:74
	v_fmac_f32_e32 v78, v49, v49
	v_fmac_f32_e32 v78, v48, v48
	s_waitcnt lgkmcnt(0)
	v_fma_f32 v23, v26, v0, -v24
	v_fma_f32 v22, v27, v0, -v25
	ds_read2st64_b32 v[24:25], v77 offset0:75 offset1:76
	ds_read2st64_b32 v[26:27], v77 offset0:77 offset1:78
	v_fmac_f32_e32 v78, v23, v23
	v_fmac_f32_e32 v78, v22, v22
	s_waitcnt lgkmcnt(1)
	v_fma_f32 v28, v28, v0, -v24
	s_waitcnt lgkmcnt(0)
	v_fma_f32 v26, v30, v0, -v26
	v_fma_f32 v24, v31, v0, -v27
	ds_read2st64_b32 v[30:31], v77 offset0:79 offset1:80
	v_fmac_f32_e32 v78, v28, v28
	v_fma_f32 v25, v29, v0, -v25
	v_fmac_f32_e32 v78, v25, v25
	v_fmac_f32_e32 v78, v26, v26
	s_waitcnt lgkmcnt(0)
; __device__ __forceinline__ unsigned pk_bf16(float lo, float hi) { return pg8::cvt_pk_bf16(lo, hi); }
; template <int DV, int NMAP>
; __device__ __forceinline__ void attn_unit(LAS unsigned char* lds, const bf16_t* U, bf16_t* MIX, const float* logf, int b, int h, int qb, float lam, float slope2, const float* gn, float outscale, const int tid) {
;     ...
;             float ss = 0.f;
; #pragma unroll
;             for (int d = 0; d < NDB; ++d)
; #pragma unroll
;                 for (int r = 0; r < 16; ++r) { const float v = o[d][r] * inv - ex[(d * 16 + r) * 64]; o[d][r] = v; ss += v * v; }
;             ss += __shfl_xor(ss, 32);
;             const float rn = outscale / sqrtf(ss * (1.0f / 128.0f) + EPS);
; #pragma unroll
;             for (int d = 0; d < NDB; ++d)
; #pragma unroll
;                 for (int g = 0; g < 4; ++g) { const f32x4 gv = *(const f32x4*)(gn + 32 * d + 8 * g + 4 * hi);
;                     u32x2 w; w.x = pk_bf16(o[d][4 * g] * rn * gv[0], o[d][4 * g + 1] * rn * gv[1]); w.y = pk_bf16(o[d][4 * g + 2] * rn * gv[2], o[d][4 * g + 3] * rn * gv[3]);
;                     *(u32x2*)(MIX + orow + 512 + 128 * h + 32 * d + 8 * g + 4 * hi) = w; }
	v_fma_f32 v76, v32, v0, -v30
	v_fma_f32 v74, v33, v0, -v31
	ds_read2st64_b32 v[30:31], v77 offset0:81 offset1:82
	v_fmac_f32_e32 v78, v24, v24
	v_fmac_f32_e32 v78, v76, v76
	v_fmac_f32_e32 v78, v74, v74
	s_waitcnt lgkmcnt(0)
	v_fma_f32 v32, v2, v0, -v30
	v_fma_f32 v31, v3, v0, -v31
	ds_read2st64_b32 v[2:3], v77 offset0:83 offset1:84
	v_fmac_f32_e32 v78, v32, v32
	v_fmac_f32_e32 v78, v31, v31
	s_waitcnt lgkmcnt(0)
	v_fma_f32 v75, v4, v0, -v2
	v_fma_f32 v72, v5, v0, -v3
	ds_read2st64_b32 v[2:3], v77 offset0:85 offset1:86
	v_fmac_f32_e32 v78, v75, v75
	v_fmac_f32_e32 v78, v72, v72
	s_waitcnt lgkmcnt(0)
	v_fma_f32 v73, v6, v0, -v2
	v_fma_f32 v70, v7, v0, -v3
	ds_read2st64_b32 v[2:3], v77 offset0:87 offset1:88
	v_fmac_f32_e32 v78, v73, v73
	v_fmac_f32_e32 v78, v70, v70
	s_waitcnt lgkmcnt(0)
	v_fma_f32 v71, v8, v0, -v2
	v_fma_f32 v33, v9, v0, -v3
	ds_read2st64_b32 v[2:3], v77 offset0:89 offset1:90
	v_fmac_f32_e32 v78, v71, v71
	v_fmac_f32_e32 v78, v33, v33
	s_waitcnt lgkmcnt(0)
	v_fma_f32 v30, v10, v0, -v2
	v_fma_f32 v29, v11, v0, -v3
	ds_read2st64_b32 v[2:3], v77 offset0:91 offset1:92
	v_fmac_f32_e32 v78, v30, v30
	v_fmac_f32_e32 v78, v29, v29
	s_waitcnt lgkmcnt(0)
	v_fma_f32 v27, v12, v0, -v2
	v_fma_f32 v13, v13, v0, -v3
	ds_read2st64_b32 v[2:3], v77 offset0:93 offset1:94
	v_fmac_f32_e32 v78, v27, v27
	v_fmac_f32_e32 v78, v13, v13
	s_waitcnt lgkmcnt(0)
	v_pk_fma_f32 v[8:9], v[14:15], v[0:1], v[2:3] op_sel_hi:[1,0,1] neg_lo:[0,0,1] neg_hi:[0,0,1]
	s_nop 0
	v_pk_mul_f32 v[2:3], v[8:9], v[8:9]
	s_nop 0
	v_add_f32_e32 v2, v78, v2
	v_add_f32_e32 v4, v2, v3
	ds_read2st64_b32 v[2:3], v77 offset0:95 offset1:96
	s_waitcnt lgkmcnt(0)
	v_pk_fma_f32 v[6:7], v[16:17], v[0:1], v[2:3] op_sel_hi:[1,0,1] neg_lo:[0,0,1] neg_hi:[0,0,1]
	s_nop 0
	v_pk_mul_f32 v[2:3], v[6:7], v[6:7]
	s_nop 0
	v_add_f32_e32 v0, v4, v2
	v_add_f32_e32 v0, v0, v3
	ds_bpermute_b32 v2, v224, v0
	s_waitcnt lgkmcnt(0)
	v_add_f32_e32 v0, v0, v2
	v_fmamk_f32 v0, v0, 0x3c000000, v225
	v_cmp_gt_f32_e64 s[40:41], s16, v0
	v_mul_f32_e32 v2, 0x4f800000, v0
	s_nop 0
	v_cndmask_b32_e64 v0, v0, v2, s[40:41]
	v_sqrt_f32_e32 v2, v0
	s_nop 0
	v_add_u32_e32 v3, -1, v2
	v_fma_f32 v4, -v3, v2, v0
	v_cmp_ge_f32_e32 vcc, 0, v4
	v_add_u32_e32 v4, 1, v2
	s_nop 0
	v_cndmask_b32_e32 v3, v2, v3, vcc
	v_fma_f32 v2, -v4, v2, v0
	v_cmp_lt_f32_e32 vcc, 0, v2
	s_nop 1
	v_cndmask_b32_e32 v2, v3, v4, vcc
	v_mul_f32_e32 v3, 0x37800000, v2
	v_cndmask_b32_e64 v2, v2, v3, s[40:41]
	v_cmp_class_f32_e32 vcc, v0, v226
	s_nop 1
	v_cndmask_b32_e32 v0, v2, v0, vcc
	v_div_scale_f32 v2, s[30:31], v0, v0, v144
	v_rcp_f32_e32 v3, v2
	v_readlane_b32 s30, v250, 34
	v_readlane_b32 s31, v250, 35
	v_fma_f32 v4, -v2, v3, 1.0
	v_fmac_f32_e32 v3, v4, v3
	v_div_scale_f32 v4, vcc, v144, v0, v144
	v_mul_f32_e32 v5, v4, v3
	v_fma_f32 v10, -v2, v5, v4
	v_fmac_f32_e32 v5, v10, v3
	v_fma_f32 v2, -v2, v5, v4
	v_div_fmas_f32 v2, v2, v3, v5
	v_div_fixup_f32 v12, v2, v0, v144
	v_lshlrev_b32_e32 v0, 11, v147
	v_lshl_add_u64 v[2:3], s[30:31], 0, v[0:1]
	v_lshl_add_u64 v[2:3], v[2:3], 0, s[20:21]
	v_lshlrev_b32_e32 v0, 1, v130
	v_lshl_add_u64 v[10:11], v[2:3], 0, v[0:1]
	v_lshl_add_u64 v[10:11], v[10:11], 0, v[0:1]
	s_waitcnt vmcnt(0)
	v_mov_b32_e32 v2, v80
	v_mov_b32_e32 v3, v81
	v_mov_b32_e32 v4, v82
	v_mov_b32_e32 v5, v83
	v_mul_f32_e32 v0, v66, v12
	v_mul_f32_e32 v0, v2, v0
	v_mul_f32_e32 v2, v50, v12
	v_mul_f32_e32 v2, v3, v2
	v_mul_f32_e32 v3, v52, v12
	v_cvt_pk_bf16_f32 v176, v0, v2
	v_mul_f32_e32 v0, v51, v12
	v_mul_f32_e32 v3, v5, v3
	v_mul_f32_e32 v0, v4, v0
	v_cvt_pk_bf16_f32 v177, v0, v3
	v_mov_b32_e32 v2, v84
	v_mov_b32_e32 v3, v85
	v_mov_b32_e32 v4, v86
	v_mov_b32_e32 v5, v87
	v_mul_f32_e32 v0, v53, v12
	v_mul_f32_e32 v0, v2, v0
	v_mul_f32_e32 v2, v54, v12
	v_mul_f32_e32 v2, v3, v2
	v_mul_f32_e32 v3, v56, v12
	v_cvt_pk_bf16_f32 v178, v0, v2
	v_mul_f32_e32 v0, v55, v12
	v_mul_f32_e32 v3, v5, v3
	v_mul_f32_e32 v0, v4, v0
	v_cvt_pk_bf16_f32 v179, v0, v3
	s_nop 1
	v_permlane32_swap_b32_e32 v176, v178
	v_permlane32_swap_b32_e32 v177, v179
	global_store_dwordx4 v[10:11], v[176:179], off offset:1024 sc1
	v_mov_b32_e32 v2, v88
	v_mov_b32_e32 v3, v89
	v_mov_b32_e32 v4, v90
	v_mov_b32_e32 v5, v91
	v_mul_f32_e32 v0, v58, v12
	v_mul_f32_e32 v0, v0, v2
	v_mul_f32_e32 v2, v57, v12
	v_mul_f32_e32 v2, v2, v3
	v_mul_f32_e32 v3, v60, v12
	v_cvt_pk_bf16_f32 v176, v0, v2
	v_mul_f32_e32 v0, v67, v12
	v_mul_f32_e32 v3, v3, v5
	v_mul_f32_e32 v0, v0, v4
	v_cvt_pk_bf16_f32 v177, v0, v3
	v_mov_b32_e32 v2, v92
	v_mov_b32_e32 v3, v93
	v_mov_b32_e32 v4, v94
	v_mov_b32_e32 v5, v95
	v_mul_f32_e32 v0, v61, v12
	v_mul_f32_e32 v0, v0, v2
	v_mul_f32_e32 v2, v59, v12
	v_mul_f32_e32 v2, v2, v3
	v_mul_f32_e32 v3, v63, v12
	v_cvt_pk_bf16_f32 v178, v0, v2
	v_mul_f32_e32 v0, v68, v12
	v_mul_f32_e32 v3, v3, v5
	v_mul_f32_e32 v0, v0, v4
	v_cvt_pk_bf16_f32 v179, v0, v3
	s_nop 1
	v_permlane32_swap_b32_e32 v176, v178
	v_permlane32_swap_b32_e32 v177, v179
	global_store_dwordx4 v[10:11], v[176:179], off offset:1056 sc1
	v_mov_b32_e32 v2, v96
	v_mov_b32_e32 v3, v97
	v_mov_b32_e32 v4, v98
	v_mov_b32_e32 v5, v99
	v_mul_f32_e32 v0, v62, v12
	v_mul_f32_e32 v0, v0, v2
	v_mul_f32_e32 v2, v34, v12
	v_mul_f32_e32 v2, v2, v3
	v_mul_f32_e32 v3, v36, v12
; __device__ __forceinline__ unsigned pk_bf16(float lo, float hi) { return pg8::cvt_pk_bf16(lo, hi); }
; template <int DV, int NMAP>
; __device__ __forceinline__ void attn_unit(LAS unsigned char* lds, const bf16_t* U, bf16_t* MIX, const float* logf, int b, int h, int qb, float lam, float slope2, const float* gn, float outscale, const int tid) {
;     ...
; #pragma unroll
;             for (int d = 0; d < NDB; ++d)
; #pragma unroll
;                 for (int g = 0; g < 4; ++g) { const f32x4 gv = *(const f32x4*)(gn + 32 * d + 8 * g + 4 * hi);
;                     u32x2 w; w.x = pk_bf16(o[d][4 * g] * rn * gv[0], o[d][4 * g + 1] * rn * gv[1]); w.y = pk_bf16(o[d][4 * g + 2] * rn * gv[2], o[d][4 * g + 3] * rn * gv[3]);
;                     *(u32x2*)(MIX + orow + 512 + 128 * h + 32 * d + 8 * g + 4 * hi) = w; }
	v_cvt_pk_bf16_f32 v176, v0, v2
	v_mul_f32_e32 v0, v64, v12
	v_mul_f32_e32 v3, v3, v5
	v_mul_f32_e32 v0, v0, v4
	v_cvt_pk_bf16_f32 v177, v0, v3
	v_mov_b32_e32 v2, v100
	v_mov_b32_e32 v3, v101
	v_mov_b32_e32 v4, v102
	v_mov_b32_e32 v5, v103
	v_mul_f32_e32 v0, v37, v12
	v_mul_f32_e32 v0, v0, v2
	v_mul_f32_e32 v2, v35, v12
	v_mul_f32_e32 v2, v2, v3
	v_mul_f32_e32 v3, v65, v12
	v_cvt_pk_bf16_f32 v178, v0, v2
	v_mul_f32_e32 v0, v69, v12
	v_mul_f32_e32 v3, v3, v5
	v_mul_f32_e32 v0, v0, v4
	v_cvt_pk_bf16_f32 v179, v0, v3
	s_nop 1
	v_permlane32_swap_b32_e32 v176, v178
	v_permlane32_swap_b32_e32 v177, v179
	global_store_dwordx4 v[10:11], v[176:179], off offset:1088 sc1
	v_mov_b32_e32 v2, v104
	v_mov_b32_e32 v3, v105
	v_mov_b32_e32 v4, v106
	v_mov_b32_e32 v5, v107
	v_mul_f32_e32 v0, v39, v12
	v_mul_f32_e32 v0, v0, v2
	v_mul_f32_e32 v2, v38, v12
	v_mul_f32_e32 v2, v2, v3
	v_mul_f32_e32 v3, v41, v12
	v_cvt_pk_bf16_f32 v176, v0, v2
	v_mul_f32_e32 v0, v43, v12
	v_mul_f32_e32 v3, v3, v5
	v_mul_f32_e32 v0, v0, v4
	v_cvt_pk_bf16_f32 v177, v0, v3
	v_mov_b32_e32 v2, v108
	v_mov_b32_e32 v3, v109
	v_mov_b32_e32 v4, v110
	v_mov_b32_e32 v5, v111
	v_mul_f32_e32 v0, v42, v12
	v_mul_f32_e32 v0, v0, v2
	v_mul_f32_e32 v2, v40, v12
	v_mul_f32_e32 v2, v2, v3
	v_mul_f32_e32 v3, v45, v12
	v_cvt_pk_bf16_f32 v178, v0, v2
	v_mul_f32_e32 v0, v47, v12
	v_mul_f32_e32 v3, v3, v5
	v_mul_f32_e32 v0, v0, v4
	v_cvt_pk_bf16_f32 v179, v0, v3
	s_nop 1
	v_permlane32_swap_b32_e32 v176, v178
	v_permlane32_swap_b32_e32 v177, v179
	global_store_dwordx4 v[10:11], v[176:179], off offset:1120 sc1
	v_mov_b32_e32 v2, v112
	v_mov_b32_e32 v3, v113
	v_mov_b32_e32 v4, v114
	v_mov_b32_e32 v5, v115
	v_mul_f32_e32 v0, v44, v12
	v_mul_f32_e32 v0, v0, v2
	v_mul_f32_e32 v2, v18, v12
	v_mul_f32_e32 v2, v2, v3
	v_mul_f32_e32 v3, v20, v12
	v_cvt_pk_bf16_f32 v176, v0, v2
	v_mul_f32_e32 v0, v46, v12
	v_mul_f32_e32 v3, v3, v5
	v_mul_f32_e32 v0, v0, v4
	v_cvt_pk_bf16_f32 v177, v0, v3
	v_mov_b32_e32 v2, v116
	v_mov_b32_e32 v3, v117
	v_mov_b32_e32 v4, v118
	v_mov_b32_e32 v5, v119
	v_mul_f32_e32 v0, v21, v12
	v_mul_f32_e32 v0, v0, v2
	v_mul_f32_e32 v2, v19, v12
	v_mul_f32_e32 v2, v2, v3
	v_mul_f32_e32 v3, v48, v12
	v_cvt_pk_bf16_f32 v178, v0, v2
	v_mul_f32_e32 v0, v49, v12
	v_mul_f32_e32 v3, v3, v5
	v_mul_f32_e32 v0, v0, v4
	v_cvt_pk_bf16_f32 v179, v0, v3
	s_nop 1
	v_permlane32_swap_b32_e32 v176, v178
	v_permlane32_swap_b32_e32 v177, v179
	global_store_dwordx4 v[10:11], v[176:179], off offset:1152 sc1
	v_mov_b32_e32 v2, v152
	v_mov_b32_e32 v3, v153
	v_mov_b32_e32 v4, v154
	v_mov_b32_e32 v5, v155
	v_mul_f32_e32 v0, v23, v12
	v_mul_f32_e32 v0, v0, v2
	v_mul_f32_e32 v2, v22, v12
	v_mul_f32_e32 v2, v2, v3
	v_mul_f32_e32 v3, v25, v12
	v_cvt_pk_bf16_f32 v176, v0, v2
	v_mul_f32_e32 v0, v28, v12
	v_mul_f32_e32 v3, v3, v5
	v_mul_f32_e32 v0, v0, v4
	v_cvt_pk_bf16_f32 v177, v0, v3
	v_mov_b32_e32 v2, v156
	v_mov_b32_e32 v3, v157
	v_mov_b32_e32 v4, v158
	v_mov_b32_e32 v5, v159
	v_mul_f32_e32 v0, v26, v12
	v_mul_f32_e32 v0, v0, v2
	v_mul_f32_e32 v2, v24, v12
	v_mul_f32_e32 v2, v2, v3
	v_mul_f32_e32 v3, v74, v12
	v_cvt_pk_bf16_f32 v178, v0, v2
	v_mul_f32_e32 v0, v76, v12
	v_mul_f32_e32 v3, v3, v5
	v_mul_f32_e32 v0, v0, v4
	v_cvt_pk_bf16_f32 v179, v0, v3
	s_nop 1
	v_permlane32_swap_b32_e32 v176, v178
	v_permlane32_swap_b32_e32 v177, v179
	global_store_dwordx4 v[10:11], v[176:179], off offset:1184 sc1
	v_mov_b32_e32 v2, v160
	v_mov_b32_e32 v3, v161
	v_mov_b32_e32 v4, v162
	v_mov_b32_e32 v5, v163
	v_mul_f32_e32 v0, v32, v12
	v_mul_f32_e32 v0, v0, v2
	v_mul_f32_e32 v2, v31, v12
	v_mul_f32_e32 v2, v2, v3
	v_mul_f32_e32 v3, v72, v12
	v_cvt_pk_bf16_f32 v176, v0, v2
	v_mul_f32_e32 v0, v75, v12
	v_mul_f32_e32 v3, v3, v5
	v_mul_f32_e32 v0, v0, v4
	v_cvt_pk_bf16_f32 v177, v0, v3
	v_mov_b32_e32 v2, v164
	v_mov_b32_e32 v3, v165
	v_mov_b32_e32 v4, v166
	v_mov_b32_e32 v5, v167
	v_mul_f32_e32 v0, v73, v12
	v_mul_f32_e32 v0, v0, v2
	v_mul_f32_e32 v2, v70, v12
	v_mul_f32_e32 v2, v2, v3
	v_mul_f32_e32 v3, v33, v12
	v_cvt_pk_bf16_f32 v178, v0, v2
	v_mul_f32_e32 v0, v71, v12
	v_mul_f32_e32 v3, v3, v5
	v_mul_f32_e32 v0, v0, v4
	v_cvt_pk_bf16_f32 v179, v0, v3
	s_nop 1
	v_permlane32_swap_b32_e32 v176, v178
	v_permlane32_swap_b32_e32 v177, v179
	global_store_dwordx4 v[10:11], v[176:179], off offset:1216 sc1
	v_mov_b32_e32 v2, v168
	v_mov_b32_e32 v3, v169
	v_mov_b32_e32 v4, v170
	v_mov_b32_e32 v5, v171
	v_mul_f32_e32 v0, v30, v12
	v_mul_f32_e32 v0, v0, v2
	v_mul_f32_e32 v2, v29, v12
	v_mul_f32_e32 v2, v2, v3
	v_mul_f32_e32 v3, v13, v12
	v_cvt_pk_bf16_f32 v176, v0, v2
	v_mul_f32_e32 v0, v27, v12
	v_mul_f32_e32 v3, v3, v5
	v_mul_f32_e32 v0, v0, v4
	v_cvt_pk_bf16_f32 v177, v0, v3
	v_mov_b32_e32 v2, v172
	v_mov_b32_e32 v3, v173
	v_mov_b32_e32 v4, v174
	v_mov_b32_e32 v5, v175
	v_mul_f32_e32 v0, v8, v12
	v_mul_f32_e32 v0, v0, v2
	v_mul_f32_e32 v2, v9, v12
	v_mul_f32_e32 v2, v2, v3
	v_mul_f32_e32 v3, v7, v12
	v_cvt_pk_bf16_f32 v178, v0, v2
	v_mul_f32_e32 v0, v6, v12
	v_mul_f32_e32 v3, v3, v5
	v_mul_f32_e32 v0, v0, v4
	v_cvt_pk_bf16_f32 v179, v0, v3
	s_nop 1
	v_permlane32_swap_b32_e32 v176, v178
	v_permlane32_swap_b32_e32 v177, v179
	global_store_dwordx4 v[10:11], v[176:179], off offset:1248 sc1
	s_branch .LBB0_175
